# epilogues: lane permute (ds_bpermute) so consecutive lanes access consecutive 16B chunks of a row - coalesced bf16 stores in the relu2 path and coalesced f32 RMW in the residual epilogues; serpentine
# speedup vs baseline: 1.0192x; 1.0074x over previous
; #define PG8_WAIT_V(n) asm volatile("s_waitcnt vmcnt(" #n ")" ::: "memory")
; #define PG8_BAR __builtin_amdgcn_s_barrier()
; __device__ __forceinline__ void gemm_phase(const Ctx& cx, LAS unsigned char* lds, const GemmDesc& g) {
;   const int tid = cx.tid_(), wid = __builtin_amdgcn_readfirstlane(tid >> 6), lane = tid & 63, wr = wid >> 2, wc = wid & 3, fr = lane & 15, fq = lane >> 4;
;   const int nt = g.nt, ksplit = g.ksplit; const bool perm = g.mode <= 2;
;   unsigned voffA[2], voffB[2];
; #pragma unroll
;   for (int i = 0; i < 2; ++i) { int R, C; stage_rc(tid * 16 + i * 8192, R, C); const int Rb = perm ? ((R & ~31) + perm32(R & 31)) : R;
;     voffA[i] = g.chunked ? (unsigned)((R >> 4) * 65536 + (R & 15) * 32 + (C >> 4) * 512 + (C & 15) * 2) : ((unsigned)R * g.rowStrideA + (unsigned)(C * 2)); voffB[i] = (unsigned)Rb * g.ldbBytes + (unsigned)(C * 2); }
;   const size_t kstepA = g.chunked ? 2048 : 128, kstepB = 128;
;   const size_t hstepA = (size_t)HALF * g.rowStrideA, hstepB = (size_t)HALF * g.ldbBytes, tstepA = 2 * hstepA, tstepB = 2 * hstepB;
;   const unsigned ldsw = (unsigned)wid * 1024u;
;   const int aoff = lds_byte(wr * 64 + fr, fq * 8), boff = lds_byte(wc * 32 + fr, fq * 8);
;     ...
;   StaticOrder S; S.init(g.nM, g.nN, (int)cx.G, (int)cx.bid, g.wgm);
;   Unit cur, nxt; int ui = 0;
;   if (!S.next(0, cur)) return;
;   f32x4 acc[2][2][4][2];
; #pragma unroll
;   for (int a = 0; a < 2; ++a)
; #pragma unroll
;     for (int b = 0; b < 2; ++b)
; #pragma unroll
;       for (int m = 0; m < 4; ++m)
; #pragma unroll
;         for (int n = 0; n < 2; ++n) acc[a][b][m][n] = (f32x4){0.f, 0.f, 0.f, 0.f};
;   bf16x8 At[4][2], B0[2][2], B1[2][2];
;   size_t aoffu = (size_t)cur.pm * tstepA + (size_t)(cur.pn >> g.pnShift) * g.pnStrideA;
;   const char* cA1 = g.A + aoffu; const char* cA2 = g.A2 + aoffu; const char* cB = g.Bt + (size_t)cur.pn * tstepB;
;   {
;     const char* a0 = ktile_ptr(cA1, cA2, 0, ksplit, kstepA); const char* a1 = ktile_ptr(cA1, cA2, 1, ksplit, kstepA);
;     PG8_STAGE(PG8_SB(0, 0), cB, voffB); PG8_STAGE(PG8_SB(0, 1), cB + hstepB, voffB); PG8_STAGE(PG8_SA(0, 0), a0, voffA); PG8_STAGE(PG8_SA(0, 1), a0 + hstepA, voffA);
;     if (wr == 1) PG8_BAR;
;     PG8_WAIT_V(2); PG8_BAR;
;     PG8_STAGE(PG8_SB(1, 0), cB + kstepB, voffB); PG8_STAGE(PG8_SA(1, 0), a1, voffA); PG8_STAGE(PG8_SB(1, 1), cB + hstepB + kstepB, voffB);
;     PG8_WAIT_V(6); PG8_BAR;
;   }
.LBB0_348:
	s_xor_b64 s[0:1], s[0:1], -1
	v_writelane_b32 v255, s0, 15
	v_and_b32_e32 v10, 15, v9
	v_bfe_u32 v11, v9, 4, 2
	v_writelane_b32 v255, s1, 16
	s_and_b64 s[0:1], s[68:69], exec
	s_cselect_b32 s80, 7, 11
	s_lshl_b64 s[68:69], 1, s80
	s_add_u32 s6, s8, s68
	v_and_b32_e32 v12, 48, v9
	v_lshlrev_b32_e32 v9, 2, v9
	s_addc_u32 s7, s9, s69
	v_lshl_or_b32 v251, s5, 6, v10
	s_lshl_b32 s0, s5, 13
	v_lshl_or_b32 v10, v10, 6, v12
	v_and_b32_e32 v9, 32, v9
	v_bitop3_b32 v12, v10, s0, v9 bitop3:0xde
	s_lshl_b32 s0, s4, 5
	s_and_b32 s4, s0, 0x60
	s_lshl_b32 s0, s4, 7
	s_add_i32 m0, s51, 0x18000
	v_lshl_add_u64 v[0:1], v[0:1], 0, s[92:93]
	v_mov_b32_e32 v211, v97
	v_bitop3_b32 v252, s0, v10, v9 bitop3:0xf6
	s_waitcnt vmcnt(2)
	s_barrier
	global_load_lds_dwordx4 v[0:1], off
	v_lshl_add_u64 v[0:1], v[2:3], 0, s[92:93]
	s_add_i32 m0, s51, 0x1a000
	s_add_i32 s0, s51, 0x8000
	v_mov_b32_e32 v213, v97
	global_load_lds_dwordx4 v[0:1], off
	v_lshl_add_u64 v[0:1], s[6:7], 0, v[210:211]
	s_mov_b32 m0, s0
	s_add_i32 s1, s51, 0xa000
	global_load_lds_dwordx4 v[0:1], off
	v_lshl_add_u64 v[0:1], s[6:7], 0, v[212:213]
	s_mov_b32 m0, s1
	s_ashr_i32 s5, s96, 31
	global_load_lds_dwordx4 v[0:1], off
	s_add_i32 m0, s51, 0x1c000
	v_lshl_add_u64 v[0:1], v[4:5], 0, s[92:93]
	global_load_lds_dwordx4 v[0:1], off
	v_lshl_add_u64 v[0:1], v[6:7], 0, s[92:93]
	s_add_i32 m0, s51, 0x1e000
	v_writelane_b32 v255, s5, 17
	global_load_lds_dwordx4 v[0:1], off
	s_lshr_b32 s5, s2, 3
	s_add_i32 s39, s10, -2
	s_cmpk_lt_u32 s12, 0x100
	v_writelane_b32 v255, s5, 18
	s_cselect_b64 s[6:7], -1, 0
	v_writelane_b32 v255, s6, 19
	v_rcp_iflag_f32_e32 v0, v8
	v_mbcnt_lo_u32_b32 v253, -1, 0
	v_mbcnt_hi_u32_b32 v253, -1, v253
	v_and_b32_e32 v253, 3, v253
	v_lshl_or_b32 v253, v253, 2, s4
	v_writelane_b32 v255, s7, 20
	v_readlane_b32 s6, v254, 60
	s_lshl_b32 s5, s6, 11
	v_writelane_b32 v255, s5, 21
	s_addk_i32 s5, 0xf800
	v_writelane_b32 v255, s5, 22
	s_and_b32 s5, s11, 1
	v_readlane_b32 s7, v254, 61
	s_cmp_eq_u32 s5, 0
	s_cselect_b64 s[6:7], -1, 0
	v_writelane_b32 v255, s6, 23
	s_cmp_eq_u32 s5, 1
	v_mul_f32_e32 v0, 0x4f7ffffe, v0
	v_writelane_b32 v255, s7, 24
	s_cselect_b64 s[6:7], -1, 0
	v_cvt_u32_f32_e32 v0, v0
	v_writelane_b32 v255, s6, 25
	s_cmp_gt_u32 s11, 31
	v_lshl_or_b32 v246, v11, 3, s4
	v_writelane_b32 v255, s7, 26
	s_cselect_b64 s[6:7], -1, 0
	v_writelane_b32 v255, s6, 27
	s_bitcmp1_b32 s11, 3
	v_readfirstlane_b32 s5, v0
	v_writelane_b32 v255, s7, 28
	s_cselect_b64 s[6:7], -1, 0
	s_sub_i32 s4, 0, s50
	s_mul_i32 s4, s4, s5
	s_waitcnt vmcnt(6)
	v_writelane_b32 v255, s6, 29
	s_mul_hi_u32 s4, s5, s4
	s_add_i32 s4, s5, s4
	v_writelane_b32 v255, s7, 30
	s_mov_b32 s81, 0
	v_writelane_b32 v255, s4, 31
	v_add_u32_e32 v237, 0, v12
	s_barrier
	s_branch .LBB0_351

; __device__ __forceinline__ void gemm_epilogue(const GemmDesc& g, const f32x4 (&acc)[2][2][4][2], const Unit& u, int wr, int wc, int fr, int fq, int lane) {
;     ...
;   } else if (g.mode == 3 || g.mode == 4) {
;     float* X = (float*)g.out; const int col0 = u.pn * BM + wc * 32 + 4 * fq; const bool ln = e_stats != nullptr || e_accIn != nullptr;
;     f32x4 cs[2][2], lg[2][2], lb[2][2];
; #pragma unroll
;     for (int bj = 0; bj < 2; ++bj)
; #pragma unroll
;       for (int n = 0; n < 2; ++n) { cs[bj][n] = (g.mode == 4) ? *(const f32x4*)(e_cscale + col0 + bj * HALF + n * 16) : (f32x4){1.f, 1.f, 1.f, 1.f};
;         lg[bj][n] = ln ? *(const f32x4*)(e_lng + col0 + bj * HALF + n * 16) : (f32x4){1.f, 1.f, 1.f, 1.f}; lb[bj][n] = ln ? *(const f32x4*)(e_lnb + col0 + bj * HALF + n * 16) : (f32x4){0.f, 0.f, 0.f, 0.f}; }
;     f32x2 st[2]; f32x4 xv[2][4];
;     const f32x2* const e_sp = e_accIn ? (const f32x2*)e_accIn : (e_stats ? e_stats : (const f32x2*)(ws_ + WS_ONE));
;     ...
;     RES_LOAD(0, 0);
; #pragma unroll
;     for (int gi = 0; gi < 8; ++gi) { const int ai = gi >> 2, m = gi & 3; const int row = row0 + ai * HALF + m * 16; float* rowp = X + (size_t)row * DM + col0;
;       if (gi + 1 < 8) RES_LOAD(gi + 1, (gi + 1) & 1);
;       float ssum = 0.f, ssq = 0.f; f32x2 sm = st[gi & 1];
;       if (e_accIn) { const float mean = sm.x * (1.0f / DM); sm = (f32x2){mean, rsqrtf(fmaxf(sm.y * (1.0f / DM) - mean * mean, 0.f) + LN_EPS)}; }
; #pragma unroll
;       for (int bj = 0; bj < 2; ++bj)
; #pragma unroll
;         for (int n = 0; n < 2; ++n) { f32x4* p = (f32x4*)(rowp + bj * HALF + n * 16); const f32x4 x = ((xv[gi & 1][bj * 2 + n] - sm.x) * sm.y) * lg[bj][n] + lb[bj][n]; const f32x4 o = x * ALPHA + acc[ai][bj][m][n] * cs[bj][n]; *p = o;
;           if (e_accOut) { ssum += (o[0] + o[1]) + (o[2] + o[3]); ssq += (o[0] * o[0] + o[1] * o[1]) + (o[2] * o[2] + o[3] * o[3]);
;             u32x2 w; w.x = cvt_pk_bf16(o[0], o[1]); w.y = cvt_pk_bf16(o[2], o[3]); *(u32x2*)(e_xbOut + (size_t)row * DM + col0 + bj * HALF + n * 16) = w; } }
;       if (e_accOut) row_emit(e_accOut, row, ssum, ssq, lane, fq); }
;     ...
;   } else if (g.mode == 5) {
;     float* X = (float*)g.out; const int col0 = u.pn * HALF + wc * 32 + 4 * fq; const bool ln = e_stats != nullptr;
;     f32x4 lg[2], lb[2];
; #pragma unroll
.LBB0_374:
	v_readlane_b32 s20, v255, 15
	v_readlane_b32 s21, v255, 16
	v_lshl_add_u32 v218, s42, 8, v251
	s_mov_b64 s[6:7], -1
	s_and_b64 vcc, exec, s[20:21]
	s_cbranch_vccz .LBB0_443
	s_waitcnt lgkmcnt(0)
	v_mbcnt_lo_u32_b32 v138, -1, 0
	v_mbcnt_hi_u32_b32 v138, -1, v138
	v_and_b32_e32 v136, 3, v138
	v_lshrrev_b32_e32 v137, 2, v138
	v_lshl_or_b32 v139, v136, 4, v137
	v_lshlrev_b32_e32 v139, 2, v139
	v_and_b32_e32 v136, 15, v138
	v_sub_u32_e32 v218, v218, v136
	v_add_u32_e32 v218, v218, v137
	ds_bpermute_b32 v0, v139, v0
	ds_bpermute_b32 v1, v139, v1
	ds_bpermute_b32 v2, v139, v2
	ds_bpermute_b32 v3, v139, v3
	ds_bpermute_b32 v4, v139, v4
	ds_bpermute_b32 v5, v139, v5
	s_waitcnt lgkmcnt(6)
	ds_bpermute_b32 v6, v139, v6
	ds_bpermute_b32 v7, v139, v7
	ds_bpermute_b32 v8, v139, v8
	ds_bpermute_b32 v9, v139, v9
	ds_bpermute_b32 v10, v139, v10
	ds_bpermute_b32 v11, v139, v11
	s_waitcnt lgkmcnt(6)
	ds_bpermute_b32 v12, v139, v12
	ds_bpermute_b32 v13, v139, v13
	ds_bpermute_b32 v14, v139, v14
	ds_bpermute_b32 v15, v139, v15
	ds_bpermute_b32 v16, v139, v16
	ds_bpermute_b32 v17, v139, v17
	s_waitcnt lgkmcnt(6)
	ds_bpermute_b32 v18, v139, v18
	ds_bpermute_b32 v19, v139, v19
	ds_bpermute_b32 v20, v139, v20
	ds_bpermute_b32 v21, v139, v21
	ds_bpermute_b32 v22, v139, v22
	ds_bpermute_b32 v23, v139, v23
	s_waitcnt lgkmcnt(6)
	ds_bpermute_b32 v24, v139, v24
	ds_bpermute_b32 v25, v139, v25
	ds_bpermute_b32 v26, v139, v26
	ds_bpermute_b32 v27, v139, v27
	ds_bpermute_b32 v28, v139, v28
	ds_bpermute_b32 v29, v139, v29
	s_waitcnt lgkmcnt(6)
	ds_bpermute_b32 v30, v139, v30
	ds_bpermute_b32 v31, v139, v31
	ds_bpermute_b32 v32, v139, v32
	ds_bpermute_b32 v33, v139, v33
	ds_bpermute_b32 v34, v139, v34
	ds_bpermute_b32 v35, v139, v35
	s_waitcnt lgkmcnt(6)
	ds_bpermute_b32 v36, v139, v36
	ds_bpermute_b32 v37, v139, v37
	ds_bpermute_b32 v38, v139, v38
	ds_bpermute_b32 v39, v139, v39
	ds_bpermute_b32 v40, v139, v40
	ds_bpermute_b32 v41, v139, v41
	s_waitcnt lgkmcnt(6)
	ds_bpermute_b32 v42, v139, v42
	ds_bpermute_b32 v43, v139, v43
	ds_bpermute_b32 v44, v139, v44
	ds_bpermute_b32 v45, v139, v45
	ds_bpermute_b32 v46, v139, v46
	ds_bpermute_b32 v47, v139, v47
	s_waitcnt lgkmcnt(6)
	ds_bpermute_b32 v48, v139, v48
	ds_bpermute_b32 v49, v139, v49
	ds_bpermute_b32 v50, v139, v50
	ds_bpermute_b32 v51, v139, v51
	ds_bpermute_b32 v52, v139, v52
	ds_bpermute_b32 v53, v139, v53
	s_waitcnt lgkmcnt(6)
	ds_bpermute_b32 v54, v139, v54
	ds_bpermute_b32 v55, v139, v55
	ds_bpermute_b32 v56, v139, v56
	ds_bpermute_b32 v57, v139, v57
	ds_bpermute_b32 v58, v139, v58
	ds_bpermute_b32 v59, v139, v59
	s_waitcnt lgkmcnt(6)
	ds_bpermute_b32 v60, v139, v60
	ds_bpermute_b32 v61, v139, v61
	ds_bpermute_b32 v62, v139, v62
	ds_bpermute_b32 v63, v139, v63
	ds_bpermute_b32 v64, v139, v64
	ds_bpermute_b32 v65, v139, v65
	s_waitcnt lgkmcnt(6)
	ds_bpermute_b32 v66, v139, v66
	ds_bpermute_b32 v67, v139, v67
	ds_bpermute_b32 v68, v139, v68
	ds_bpermute_b32 v69, v139, v69
	ds_bpermute_b32 v70, v139, v70
	ds_bpermute_b32 v71, v139, v71
	s_waitcnt lgkmcnt(6)
	ds_bpermute_b32 v72, v139, v72
	ds_bpermute_b32 v73, v139, v73
	ds_bpermute_b32 v74, v139, v74
	ds_bpermute_b32 v75, v139, v75
	ds_bpermute_b32 v76, v139, v76
	ds_bpermute_b32 v77, v139, v77
	s_waitcnt lgkmcnt(6)
	ds_bpermute_b32 v78, v139, v78
	ds_bpermute_b32 v79, v139, v79
	ds_bpermute_b32 v80, v139, v80
	ds_bpermute_b32 v81, v139, v81
	ds_bpermute_b32 v82, v139, v82
	ds_bpermute_b32 v83, v139, v83
	s_waitcnt lgkmcnt(6)
	ds_bpermute_b32 v84, v139, v84
	ds_bpermute_b32 v85, v139, v85
	ds_bpermute_b32 v86, v139, v86
	ds_bpermute_b32 v87, v139, v87
	ds_bpermute_b32 v88, v139, v88
	ds_bpermute_b32 v89, v139, v89
	s_waitcnt lgkmcnt(6)
	ds_bpermute_b32 v90, v139, v90
	ds_bpermute_b32 v91, v139, v91
	ds_bpermute_b32 v92, v139, v92
	ds_bpermute_b32 v93, v139, v93
	ds_bpermute_b32 v94, v139, v94
	ds_bpermute_b32 v95, v139, v95
	s_waitcnt lgkmcnt(6)
	ds_bpermute_b32 v98, v139, v98
	ds_bpermute_b32 v99, v139, v99
	ds_bpermute_b32 v100, v139, v100
	ds_bpermute_b32 v101, v139, v101
	ds_bpermute_b32 v102, v139, v102
	ds_bpermute_b32 v103, v139, v103
	s_waitcnt lgkmcnt(6)
	ds_bpermute_b32 v104, v139, v104
	ds_bpermute_b32 v105, v139, v105
	ds_bpermute_b32 v106, v139, v106
	ds_bpermute_b32 v107, v139, v107
	ds_bpermute_b32 v108, v139, v108
	ds_bpermute_b32 v109, v139, v109
	s_waitcnt lgkmcnt(6)
	ds_bpermute_b32 v110, v139, v110
	ds_bpermute_b32 v111, v139, v111
	ds_bpermute_b32 v112, v139, v112
	ds_bpermute_b32 v113, v139, v113
	ds_bpermute_b32 v114, v139, v114
	ds_bpermute_b32 v115, v139, v115
	s_waitcnt lgkmcnt(6)
	ds_bpermute_b32 v116, v139, v116
	ds_bpermute_b32 v117, v139, v117
	ds_bpermute_b32 v118, v139, v118
	ds_bpermute_b32 v119, v139, v119
	ds_bpermute_b32 v120, v139, v120
	ds_bpermute_b32 v121, v139, v121
	s_waitcnt lgkmcnt(6)
	ds_bpermute_b32 v122, v139, v122
	ds_bpermute_b32 v123, v139, v123
	ds_bpermute_b32 v124, v139, v124
	ds_bpermute_b32 v125, v139, v125
	ds_bpermute_b32 v126, v139, v126
	ds_bpermute_b32 v127, v139, v127
	s_waitcnt lgkmcnt(6)
	ds_bpermute_b32 v128, v139, v128
	ds_bpermute_b32 v129, v139, v129
	s_waitcnt lgkmcnt(0)
	s_add_u32 s76, s14, 0x900000
	s_addc_u32 s42, s15, 0
	v_readlane_b32 s6, v255, 10
	s_mov_b64 s[58:59], -1
	s_mov_b64 s[20:21], 0
	s_cmp_lt_i32 s6, 5
	s_mov_b64 s[6:7], 0
	s_cbranch_scc1 .LBB0_511
	v_readlane_b32 s6, v255, 10
	s_cmp_eq_u32 s6, 5
	s_mov_b64 s[6:7], -1
	s_cbranch_scc0 .LBB0_438
	v_lshl_or_b32 v130, s23, 7, v253
	v_readlane_b32 s58, v255, 25
	v_ashrrev_i32_e32 v131, 31, v130
	v_readlane_b32 s59, v255, 26
	v_lshlrev_b64 v[146:147], 2, v[130:131]
	v_mov_b32_e32 v134, 0
	v_mov_b32_e32 v130, 1.0
	v_cndmask_b32_e64 v96, 0, 1, s[58:59]
	v_lshl_add_u64 v[148:149], s[8:9], 0, v[146:147]
	v_lshl_add_u64 v[150:151], s[72:73], 0, v[146:147]
	v_cmp_ne_u32_e64 s[6:7], 1, v96
	s_andn2_b64 vcc, exec, s[58:59]
	v_mov_b32_e32 v138, 1.0
	v_mov_b32_e32 v139, v130
	v_mov_b32_e32 v140, 1.0
	v_mov_b32_e32 v141, 1.0
	v_mov_b32_e32 v142, 0
	v_mov_b32_e32 v143, v134
	v_mov_b32_e32 v144, 0
	v_mov_b32_e32 v145, 0
	s_cbranch_vccnz .LBB0_379
	global_load_dwordx4 v[138:141], v[148:149], off
	global_load_dwordx4 v[142:145], v[150:151], off

; __device__ __forceinline__ unsigned cvt_pk_bf16(float lo, float hi) { unsigned r; asm volatile("v_cvt_pk_bf16_f32 %0, %1, %2" : "=v"(r) : "v"(lo), "v"(hi)); return r; }
; __device__ __forceinline__ void gemm_epilogue(const GemmDesc& g, const f32x4 (&acc)[2][2][4][2], const Unit& u, int wr, int wc, int fr, int fq, int lane) {
;     ...
;     bf16_t* O = (bf16_t*)g.out; const int col0 = u.pn * BM + wc * 32 + 8 * fq;
;     const bool fold = (g.mode == 1) && (e_cg != nullptr);
;     f32x4 fg[2][2], fb[2][2]; f32x2 fst[8];
;     if (fold) {
; #pragma unroll
;       for (int bj = 0; bj < 2; ++bj)
; #pragma unroll
;         for (int n = 0; n < 2; ++n) { fg[bj][n] = *(const f32x4*)(e_cg + col0 + bj * HALF + 4 * n); fb[bj][n] = *(const f32x4*)(e_cb + col0 + bj * HALF + 4 * n); }
; #pragma unroll
;       for (int gi = 0; gi < 8; ++gi) fst[gi] = *(const f32x2*)(e_accIn + 2 * (size_t)(row0 + (gi >> 2) * HALF + (gi & 3) * 16));
; #pragma unroll
;       for (int gi = 0; gi < 8; ++gi) { const float mean = fst[gi].x * (1.0f / DM); fst[gi] = (f32x2){mean, rsqrtf(fmaxf(fst[gi].y * (1.0f / DM) - mean * mean, 0.f) + LN_EPS)}; }
;     }
; #pragma unroll
;     for (int ai = 0; ai < 2; ++ai)
; #pragma unroll
;       for (int m = 0; m < 4; ++m) { bf16_t* rowp = O + (size_t)(row0 + ai * HALF + m * 16) * g.ldc + col0;
; #pragma unroll
;         for (int bj = 0; bj < 2; ++bj) { f32x4 v0 = acc[ai][bj][m][0], v1 = acc[ai][bj][m][1];
;           if (g.mode == 1) {
;             if (fold) { const f32x2 st = fst[ai * 4 + m]; v0 = (v0 - fg[bj][0] * st.x) * st.y + fb[bj][0]; v1 = (v1 - fg[bj][1] * st.x) * st.y + fb[bj][1]; }
; #pragma unroll
;             for (int j = 0; j < 4; ++j) { const float a = fmaxf(v0[j], 0.f), b = fmaxf(v1[j], 0.f); v0[j] = a * a; v1[j] = b * b; } }
;           if (g.mode == 2) {
; #pragma unroll
;             for (int j = 0; j < 4; ++j) { v0[j] = gelu_tanh(v0[j]); v1[j] = gelu_tanh(v1[j]); } }
;           u32x4 w; w.x = cvt_pk_bf16(v0[0], v0[1]); w.y = cvt_pk_bf16(v0[2], v0[3]); w.z = cvt_pk_bf16(v1[0], v1[1]); w.w = cvt_pk_bf16(v1[2], v1[3]);
;           *(u32x4*)(rowp + bj * HALF) = w; } }
.Lfast_m1:
	s_waitcnt lgkmcnt(0)
	v_mbcnt_lo_u32_b32 v138, -1, 0
	v_mbcnt_hi_u32_b32 v138, -1, v138
	v_and_b32_e32 v136, 3, v138
	v_lshrrev_b32_e32 v137, 2, v138
	v_lshl_or_b32 v139, v136, 4, v137
	v_lshlrev_b32_e32 v139, 2, v139
	v_and_b32_e32 v96, 15, v138
	v_sub_u32_e32 v140, v218, v96
	v_add_u32_e32 v140, v140, v137
	v_lshrrev_b32_e32 v96, 4, v138
	v_sub_u32_e32 v96, v136, v96
	v_lshl_add_u32 v141, v96, 3, v246
	v_lshl_or_b32 v130, s23, 8, v141
	v_ashrrev_i32_e32 v96, 31, v140
	v_ashrrev_i32_e32 v131, 31, v130
	v_mul_lo_u32 v134, s27, v140
	v_mul_lo_u32 v96, s26, v96
	v_mad_u64_u32 v[132:133], vcc, s26, v140, 0
	v_lshl_add_u64 v[130:131], v[130:131], 1, s[66:67]
	s_lshl_b64 s[6:7], s[26:27], 5
	s_mul_hi_u32 s9, s26, 0xa0
	s_mul_i32 s8, s27, 0xa0
	s_add_i32 s9, s9, s8
	s_mul_i32 s8, s26, 0xa0
	v_add3_u32 v133, v133, v96, v134
	v_lshl_add_u64 v[132:133], v[132:133], 1, v[130:131]
	v_max_f32_e32 v126, 0, v126
	v_max_f32_e32 v127, 0, v127
	v_max_f32_e32 v128, 0, v128
	v_max_f32_e32 v129, 0, v129
	v_max_f32_e32 v122, 0, v122
	v_max_f32_e32 v123, 0, v123
	v_max_f32_e32 v124, 0, v124
	v_max_f32_e32 v125, 0, v125
	v_lshl_add_u64 v[134:135], v[132:133], 0, s[6:7]
	v_pk_mul_f32 v[126:127], v[126:127], v[126:127]
	v_pk_mul_f32 v[128:129], v[128:129], v[128:129]
	v_pk_mul_f32 v[122:123], v[122:123], v[122:123]
	v_pk_mul_f32 v[124:125], v[124:125], v[124:125]
	v_cvt_pk_bf16_f32 v126, v126, v127
	v_cvt_pk_bf16_f32 v127, v128, v129
	v_cvt_pk_bf16_f32 v128, v122, v123
	v_cvt_pk_bf16_f32 v129, v124, v125
	ds_bpermute_b32 v140, v139, v126
	ds_bpermute_b32 v141, v139, v127
	ds_bpermute_b32 v142, v139, v128
	ds_bpermute_b32 v143, v139, v129
	v_max_f32_e32 v118, 0, v118
	v_max_f32_e32 v119, 0, v119
	v_max_f32_e32 v120, 0, v120
	v_max_f32_e32 v121, 0, v121
	v_max_f32_e32 v114, 0, v114
	v_max_f32_e32 v115, 0, v115
	v_max_f32_e32 v116, 0, v116
	v_max_f32_e32 v117, 0, v117
	v_pk_mul_f32 v[118:119], v[118:119], v[118:119]
	v_pk_mul_f32 v[120:121], v[120:121], v[120:121]
	v_pk_mul_f32 v[114:115], v[114:115], v[114:115]
	v_pk_mul_f32 v[116:117], v[116:117], v[116:117]
	v_cvt_pk_bf16_f32 v118, v118, v119
	v_cvt_pk_bf16_f32 v119, v120, v121
	v_cvt_pk_bf16_f32 v120, v114, v115
	v_cvt_pk_bf16_f32 v121, v116, v117
	ds_bpermute_b32 v144, v139, v118
	ds_bpermute_b32 v145, v139, v119
	ds_bpermute_b32 v146, v139, v120
	ds_bpermute_b32 v147, v139, v121
	s_waitcnt lgkmcnt(4)
	global_store_dwordx4 v[132:133], v[140:143], off
	v_max_f32_e32 v110, 0, v110
	v_max_f32_e32 v111, 0, v111
	v_max_f32_e32 v112, 0, v112
	v_max_f32_e32 v113, 0, v113
	v_max_f32_e32 v106, 0, v106
	v_max_f32_e32 v107, 0, v107
	v_max_f32_e32 v108, 0, v108
	v_max_f32_e32 v109, 0, v109
	v_lshl_add_u64 v[136:137], v[134:135], 0, s[6:7]
	v_pk_mul_f32 v[110:111], v[110:111], v[110:111]
	v_pk_mul_f32 v[112:113], v[112:113], v[112:113]
	v_pk_mul_f32 v[106:107], v[106:107], v[106:107]
	v_pk_mul_f32 v[108:109], v[108:109], v[108:109]
	v_cvt_pk_bf16_f32 v110, v110, v111
	v_cvt_pk_bf16_f32 v111, v112, v113
	v_cvt_pk_bf16_f32 v112, v106, v107
	v_cvt_pk_bf16_f32 v113, v108, v109
	ds_bpermute_b32 v140, v139, v110
	ds_bpermute_b32 v141, v139, v111
	ds_bpermute_b32 v142, v139, v112
	ds_bpermute_b32 v143, v139, v113
	s_waitcnt lgkmcnt(4)
	global_store_dwordx4 v[132:133], v[144:147], off offset:256
	v_max_f32_e32 v102, 0, v102
	v_max_f32_e32 v103, 0, v103
	v_max_f32_e32 v104, 0, v104
	v_max_f32_e32 v105, 0, v105
	v_max_f32_e32 v98, 0, v98
	v_max_f32_e32 v99, 0, v99
	v_max_f32_e32 v100, 0, v100
	v_max_f32_e32 v101, 0, v101
	v_pk_mul_f32 v[102:103], v[102:103], v[102:103]
	v_pk_mul_f32 v[104:105], v[104:105], v[104:105]
	v_pk_mul_f32 v[98:99], v[98:99], v[98:99]
	v_pk_mul_f32 v[100:101], v[100:101], v[100:101]
	v_cvt_pk_bf16_f32 v102, v102, v103
	v_cvt_pk_bf16_f32 v103, v104, v105
	v_cvt_pk_bf16_f32 v104, v98, v99
	v_cvt_pk_bf16_f32 v105, v100, v101
	ds_bpermute_b32 v144, v139, v102
	ds_bpermute_b32 v145, v139, v103
	ds_bpermute_b32 v146, v139, v104
	ds_bpermute_b32 v147, v139, v105
	s_waitcnt lgkmcnt(4)
	global_store_dwordx4 v[134:135], v[140:143], off
	v_max_f32_e32 v92, 0, v92
	v_max_f32_e32 v93, 0, v93
	v_max_f32_e32 v94, 0, v94
	v_max_f32_e32 v95, 0, v95
	v_max_f32_e32 v88, 0, v88
	v_max_f32_e32 v89, 0, v89
	v_max_f32_e32 v90, 0, v90
	v_max_f32_e32 v91, 0, v91
	v_lshl_add_u64 v[132:133], v[136:137], 0, s[6:7]
	v_pk_mul_f32 v[92:93], v[92:93], v[92:93]
	v_pk_mul_f32 v[94:95], v[94:95], v[94:95]
	v_pk_mul_f32 v[88:89], v[88:89], v[88:89]
	v_pk_mul_f32 v[90:91], v[90:91], v[90:91]
	v_cvt_pk_bf16_f32 v92, v92, v93
	v_cvt_pk_bf16_f32 v93, v94, v95
	v_cvt_pk_bf16_f32 v94, v88, v89
	v_cvt_pk_bf16_f32 v95, v90, v91
	ds_bpermute_b32 v140, v139, v92
	ds_bpermute_b32 v141, v139, v93
	ds_bpermute_b32 v142, v139, v94
	ds_bpermute_b32 v143, v139, v95
	s_waitcnt lgkmcnt(4)
	global_store_dwordx4 v[134:135], v[144:147], off offset:256
	v_max_f32_e32 v84, 0, v84
	v_max_f32_e32 v85, 0, v85
	v_max_f32_e32 v86, 0, v86
	v_max_f32_e32 v87, 0, v87
	v_max_f32_e32 v80, 0, v80
	v_max_f32_e32 v81, 0, v81
	v_max_f32_e32 v82, 0, v82
	v_max_f32_e32 v83, 0, v83
	v_pk_mul_f32 v[84:85], v[84:85], v[84:85]
	v_pk_mul_f32 v[86:87], v[86:87], v[86:87]
	v_pk_mul_f32 v[80:81], v[80:81], v[80:81]
	v_pk_mul_f32 v[82:83], v[82:83], v[82:83]
	v_cvt_pk_bf16_f32 v84, v84, v85
	v_cvt_pk_bf16_f32 v85, v86, v87
	v_cvt_pk_bf16_f32 v86, v80, v81
	v_cvt_pk_bf16_f32 v87, v82, v83
	ds_bpermute_b32 v144, v139, v84
	ds_bpermute_b32 v145, v139, v85
	ds_bpermute_b32 v146, v139, v86
	ds_bpermute_b32 v147, v139, v87
	s_waitcnt lgkmcnt(4)
; __device__ __forceinline__ unsigned cvt_pk_bf16(float lo, float hi) { unsigned r; asm volatile("v_cvt_pk_bf16_f32 %0, %1, %2" : "=v"(r) : "v"(lo), "v"(hi)); return r; }
; __device__ __forceinline__ void gemm_epilogue(const GemmDesc& g, const f32x4 (&acc)[2][2][4][2], const Unit& u, int wr, int wc, int fr, int fq, int lane) {
;     ...
; #pragma unroll
;     for (int ai = 0; ai < 2; ++ai)
; #pragma unroll
;       for (int m = 0; m < 4; ++m) { bf16_t* rowp = O + (size_t)(row0 + ai * HALF + m * 16) * g.ldc + col0;
; #pragma unroll
;         for (int bj = 0; bj < 2; ++bj) { f32x4 v0 = acc[ai][bj][m][0], v1 = acc[ai][bj][m][1];
;           if (g.mode == 1) {
;             if (fold) { const f32x2 st = fst[ai * 4 + m]; v0 = (v0 - fg[bj][0] * st.x) * st.y + fb[bj][0]; v1 = (v1 - fg[bj][1] * st.x) * st.y + fb[bj][1]; }
; #pragma unroll
;             for (int j = 0; j < 4; ++j) { const float a = fmaxf(v0[j], 0.f), b = fmaxf(v1[j], 0.f); v0[j] = a * a; v1[j] = b * b; } }
;           if (g.mode == 2) {
; #pragma unroll
;             for (int j = 0; j < 4; ++j) { v0[j] = gelu_tanh(v0[j]); v1[j] = gelu_tanh(v1[j]); } }
;           u32x4 w; w.x = cvt_pk_bf16(v0[0], v0[1]); w.y = cvt_pk_bf16(v0[2], v0[3]); w.z = cvt_pk_bf16(v1[0], v1[1]); w.w = cvt_pk_bf16(v1[2], v1[3]);
;           *(u32x4*)(rowp + bj * HALF) = w; } }
	global_store_dwordx4 v[136:137], v[140:143], off
	v_max_f32_e32 v76, 0, v76
	v_max_f32_e32 v77, 0, v77
	v_max_f32_e32 v78, 0, v78
	v_max_f32_e32 v79, 0, v79
	v_max_f32_e32 v72, 0, v72
	v_max_f32_e32 v73, 0, v73
	v_max_f32_e32 v74, 0, v74
	v_max_f32_e32 v75, 0, v75
	v_lshl_add_u64 v[134:135], v[132:133], 0, s[8:9]
	v_pk_mul_f32 v[76:77], v[76:77], v[76:77]
	v_pk_mul_f32 v[78:79], v[78:79], v[78:79]
	v_pk_mul_f32 v[72:73], v[72:73], v[72:73]
	v_pk_mul_f32 v[74:75], v[74:75], v[74:75]
	v_cvt_pk_bf16_f32 v76, v76, v77
	v_cvt_pk_bf16_f32 v77, v78, v79
	v_cvt_pk_bf16_f32 v78, v72, v73
	v_cvt_pk_bf16_f32 v79, v74, v75
	ds_bpermute_b32 v140, v139, v76
	ds_bpermute_b32 v141, v139, v77
	ds_bpermute_b32 v142, v139, v78
	ds_bpermute_b32 v143, v139, v79
	s_waitcnt lgkmcnt(4)
	global_store_dwordx4 v[136:137], v[144:147], off offset:256
	v_max_f32_e32 v68, 0, v68
	v_max_f32_e32 v69, 0, v69
	v_max_f32_e32 v70, 0, v70
	v_max_f32_e32 v71, 0, v71
	v_max_f32_e32 v64, 0, v64
	v_max_f32_e32 v65, 0, v65
	v_max_f32_e32 v66, 0, v66
	v_max_f32_e32 v67, 0, v67
	v_pk_mul_f32 v[68:69], v[68:69], v[68:69]
	v_pk_mul_f32 v[70:71], v[70:71], v[70:71]
	v_pk_mul_f32 v[64:65], v[64:65], v[64:65]
	v_pk_mul_f32 v[66:67], v[66:67], v[66:67]
	v_cvt_pk_bf16_f32 v68, v68, v69
	v_cvt_pk_bf16_f32 v69, v70, v71
	v_cvt_pk_bf16_f32 v70, v64, v65
	v_cvt_pk_bf16_f32 v71, v66, v67
	ds_bpermute_b32 v144, v139, v68
	ds_bpermute_b32 v145, v139, v69
	ds_bpermute_b32 v146, v139, v70
	ds_bpermute_b32 v147, v139, v71
	s_waitcnt lgkmcnt(4)
	global_store_dwordx4 v[132:133], v[140:143], off
	v_max_f32_e32 v60, 0, v60
	v_max_f32_e32 v61, 0, v61
	v_max_f32_e32 v62, 0, v62
	v_max_f32_e32 v63, 0, v63
	v_max_f32_e32 v56, 0, v56
	v_max_f32_e32 v57, 0, v57
	v_max_f32_e32 v58, 0, v58
	v_max_f32_e32 v59, 0, v59
	v_lshl_add_u64 v[136:137], v[134:135], 0, s[6:7]
	v_pk_mul_f32 v[60:61], v[60:61], v[60:61]
	v_pk_mul_f32 v[62:63], v[62:63], v[62:63]
	v_pk_mul_f32 v[56:57], v[56:57], v[56:57]
	v_pk_mul_f32 v[58:59], v[58:59], v[58:59]
	v_cvt_pk_bf16_f32 v60, v60, v61
	v_cvt_pk_bf16_f32 v61, v62, v63
	v_cvt_pk_bf16_f32 v62, v56, v57
	v_cvt_pk_bf16_f32 v63, v58, v59
	ds_bpermute_b32 v140, v139, v60
	ds_bpermute_b32 v141, v139, v61
	ds_bpermute_b32 v142, v139, v62
	ds_bpermute_b32 v143, v139, v63
	s_waitcnt lgkmcnt(4)
	global_store_dwordx4 v[132:133], v[144:147], off offset:256
	v_max_f32_e32 v52, 0, v52
	v_max_f32_e32 v53, 0, v53
	v_max_f32_e32 v54, 0, v54
	v_max_f32_e32 v55, 0, v55
	v_max_f32_e32 v48, 0, v48
	v_max_f32_e32 v49, 0, v49
	v_max_f32_e32 v50, 0, v50
	v_max_f32_e32 v51, 0, v51
	v_pk_mul_f32 v[52:53], v[52:53], v[52:53]
	v_pk_mul_f32 v[54:55], v[54:55], v[54:55]
	v_pk_mul_f32 v[48:49], v[48:49], v[48:49]
	v_pk_mul_f32 v[50:51], v[50:51], v[50:51]
	v_cvt_pk_bf16_f32 v52, v52, v53
	v_cvt_pk_bf16_f32 v53, v54, v55
	v_cvt_pk_bf16_f32 v54, v48, v49
	v_cvt_pk_bf16_f32 v55, v50, v51
	ds_bpermute_b32 v144, v139, v52
	ds_bpermute_b32 v145, v139, v53
	ds_bpermute_b32 v146, v139, v54
	ds_bpermute_b32 v147, v139, v55
	s_waitcnt lgkmcnt(4)
	global_store_dwordx4 v[134:135], v[140:143], off
	v_max_f32_e32 v44, 0, v44
	v_max_f32_e32 v45, 0, v45
	v_max_f32_e32 v46, 0, v46
	v_max_f32_e32 v47, 0, v47
	v_max_f32_e32 v40, 0, v40
	v_max_f32_e32 v41, 0, v41
	v_max_f32_e32 v42, 0, v42
	v_max_f32_e32 v43, 0, v43
	v_lshl_add_u64 v[132:133], v[136:137], 0, s[6:7]
	v_pk_mul_f32 v[44:45], v[44:45], v[44:45]
	v_pk_mul_f32 v[46:47], v[46:47], v[46:47]
	v_pk_mul_f32 v[40:41], v[40:41], v[40:41]
	v_pk_mul_f32 v[42:43], v[42:43], v[42:43]
	v_cvt_pk_bf16_f32 v44, v44, v45
	v_cvt_pk_bf16_f32 v45, v46, v47
	v_cvt_pk_bf16_f32 v46, v40, v41
	v_cvt_pk_bf16_f32 v47, v42, v43
	ds_bpermute_b32 v140, v139, v44
	ds_bpermute_b32 v141, v139, v45
	ds_bpermute_b32 v142, v139, v46
	ds_bpermute_b32 v143, v139, v47
	s_waitcnt lgkmcnt(4)
; __device__ __forceinline__ unsigned cvt_pk_bf16(float lo, float hi) { unsigned r; asm volatile("v_cvt_pk_bf16_f32 %0, %1, %2" : "=v"(r) : "v"(lo), "v"(hi)); return r; }
; __device__ __forceinline__ void gemm_epilogue(const GemmDesc& g, const f32x4 (&acc)[2][2][4][2], const Unit& u, int wr, int wc, int fr, int fq, int lane) {
;     ...
; #pragma unroll
;     for (int ai = 0; ai < 2; ++ai)
; #pragma unroll
;       for (int m = 0; m < 4; ++m) { bf16_t* rowp = O + (size_t)(row0 + ai * HALF + m * 16) * g.ldc + col0;
; #pragma unroll
;         for (int bj = 0; bj < 2; ++bj) { f32x4 v0 = acc[ai][bj][m][0], v1 = acc[ai][bj][m][1];
;           if (g.mode == 1) {
;             if (fold) { const f32x2 st = fst[ai * 4 + m]; v0 = (v0 - fg[bj][0] * st.x) * st.y + fb[bj][0]; v1 = (v1 - fg[bj][1] * st.x) * st.y + fb[bj][1]; }
; #pragma unroll
;             for (int j = 0; j < 4; ++j) { const float a = fmaxf(v0[j], 0.f), b = fmaxf(v1[j], 0.f); v0[j] = a * a; v1[j] = b * b; } }
;           if (g.mode == 2) {
; #pragma unroll
;             for (int j = 0; j < 4; ++j) { v0[j] = gelu_tanh(v0[j]); v1[j] = gelu_tanh(v1[j]); } }
;           u32x4 w; w.x = cvt_pk_bf16(v0[0], v0[1]); w.y = cvt_pk_bf16(v0[2], v0[3]); w.z = cvt_pk_bf16(v1[0], v1[1]); w.w = cvt_pk_bf16(v1[2], v1[3]);
;           *(u32x4*)(rowp + bj * HALF) = w; } }
	global_store_dwordx4 v[134:135], v[144:147], off offset:256
	v_max_f32_e32 v36, 0, v36
	v_max_f32_e32 v37, 0, v37
	v_max_f32_e32 v38, 0, v38
	v_max_f32_e32 v39, 0, v39
	v_max_f32_e32 v32, 0, v32
	v_max_f32_e32 v33, 0, v33
	v_max_f32_e32 v34, 0, v34
	v_max_f32_e32 v35, 0, v35
	v_pk_mul_f32 v[36:37], v[36:37], v[36:37]
	v_pk_mul_f32 v[38:39], v[38:39], v[38:39]
	v_pk_mul_f32 v[32:33], v[32:33], v[32:33]
	v_pk_mul_f32 v[34:35], v[34:35], v[34:35]
	v_cvt_pk_bf16_f32 v36, v36, v37
	v_cvt_pk_bf16_f32 v37, v38, v39
	v_cvt_pk_bf16_f32 v38, v32, v33
	v_cvt_pk_bf16_f32 v39, v34, v35
	ds_bpermute_b32 v144, v139, v36
	ds_bpermute_b32 v145, v139, v37
	ds_bpermute_b32 v146, v139, v38
	ds_bpermute_b32 v147, v139, v39
	s_waitcnt lgkmcnt(4)
	global_store_dwordx4 v[136:137], v[140:143], off
	v_max_f32_e32 v28, 0, v28
	v_max_f32_e32 v29, 0, v29
	v_max_f32_e32 v30, 0, v30
	v_max_f32_e32 v31, 0, v31
	v_max_f32_e32 v24, 0, v24
	v_max_f32_e32 v25, 0, v25
	v_max_f32_e32 v26, 0, v26
	v_max_f32_e32 v27, 0, v27
	v_lshl_add_u64 v[134:135], v[132:133], 0, s[6:7]
	v_pk_mul_f32 v[28:29], v[28:29], v[28:29]
	v_pk_mul_f32 v[30:31], v[30:31], v[30:31]
	v_pk_mul_f32 v[24:25], v[24:25], v[24:25]
	v_pk_mul_f32 v[26:27], v[26:27], v[26:27]
	v_cvt_pk_bf16_f32 v28, v28, v29
	v_cvt_pk_bf16_f32 v29, v30, v31
	v_cvt_pk_bf16_f32 v30, v24, v25
	v_cvt_pk_bf16_f32 v31, v26, v27
	ds_bpermute_b32 v140, v139, v28
	ds_bpermute_b32 v141, v139, v29
	ds_bpermute_b32 v142, v139, v30
	ds_bpermute_b32 v143, v139, v31
	s_waitcnt lgkmcnt(4)
	global_store_dwordx4 v[136:137], v[144:147], off offset:256
	v_max_f32_e32 v20, 0, v20
	v_max_f32_e32 v21, 0, v21
	v_max_f32_e32 v22, 0, v22
	v_max_f32_e32 v23, 0, v23
	v_max_f32_e32 v16, 0, v16
	v_max_f32_e32 v17, 0, v17
	v_max_f32_e32 v18, 0, v18
	v_max_f32_e32 v19, 0, v19
	v_pk_mul_f32 v[20:21], v[20:21], v[20:21]
	v_pk_mul_f32 v[22:23], v[22:23], v[22:23]
	v_pk_mul_f32 v[16:17], v[16:17], v[16:17]
	v_pk_mul_f32 v[18:19], v[18:19], v[18:19]
	v_cvt_pk_bf16_f32 v20, v20, v21
	v_cvt_pk_bf16_f32 v21, v22, v23
	v_cvt_pk_bf16_f32 v22, v16, v17
	v_cvt_pk_bf16_f32 v23, v18, v19
	ds_bpermute_b32 v144, v139, v20
	ds_bpermute_b32 v145, v139, v21
	ds_bpermute_b32 v146, v139, v22
	ds_bpermute_b32 v147, v139, v23
	s_waitcnt lgkmcnt(4)
	global_store_dwordx4 v[132:133], v[140:143], off
	v_max_f32_e32 v12, 0, v12
	v_max_f32_e32 v13, 0, v13
	v_max_f32_e32 v14, 0, v14
	v_max_f32_e32 v15, 0, v15
	v_max_f32_e32 v8, 0, v8
	v_max_f32_e32 v9, 0, v9
	v_max_f32_e32 v10, 0, v10
	v_max_f32_e32 v11, 0, v11
	v_pk_mul_f32 v[12:13], v[12:13], v[12:13]
	v_pk_mul_f32 v[14:15], v[14:15], v[14:15]
	v_pk_mul_f32 v[8:9], v[8:9], v[8:9]
	v_pk_mul_f32 v[10:11], v[10:11], v[10:11]
	v_cvt_pk_bf16_f32 v12, v12, v13
	v_cvt_pk_bf16_f32 v13, v14, v15
	v_cvt_pk_bf16_f32 v14, v8, v9
	v_cvt_pk_bf16_f32 v15, v10, v11
	ds_bpermute_b32 v140, v139, v12
	ds_bpermute_b32 v141, v139, v13
	ds_bpermute_b32 v142, v139, v14
	ds_bpermute_b32 v143, v139, v15
	s_waitcnt lgkmcnt(4)
	global_store_dwordx4 v[132:133], v[144:147], off offset:256
	v_max_f32_e32 v4, 0, v4
	v_max_f32_e32 v5, 0, v5
	v_max_f32_e32 v6, 0, v6
	v_max_f32_e32 v7, 0, v7
	v_max_f32_e32 v0, 0, v0
	v_max_f32_e32 v1, 0, v1
	v_max_f32_e32 v2, 0, v2
	v_max_f32_e32 v3, 0, v3
	v_pk_mul_f32 v[4:5], v[4:5], v[4:5]
	v_pk_mul_f32 v[6:7], v[6:7], v[6:7]
	v_pk_mul_f32 v[0:1], v[0:1], v[0:1]
	v_pk_mul_f32 v[2:3], v[2:3], v[2:3]
	v_cvt_pk_bf16_f32 v4, v4, v5
	v_cvt_pk_bf16_f32 v5, v6, v7
	v_cvt_pk_bf16_f32 v6, v0, v1
	v_cvt_pk_bf16_f32 v7, v2, v3
	ds_bpermute_b32 v144, v139, v4
	ds_bpermute_b32 v145, v139, v5
	ds_bpermute_b32 v146, v139, v6
	ds_bpermute_b32 v147, v139, v7
	s_waitcnt lgkmcnt(4)
	global_store_dwordx4 v[134:135], v[140:143], off
	s_waitcnt lgkmcnt(0)
	global_store_dwordx4 v[134:135], v[144:147], off offset:256
	s_branch .Lfast_tail
